# v66 + spatial-gating item epilogue: 16 serialized u-loads batched as 2x8 prefetched loads with counted vmcnt
# baseline (speedup 1.0000x reference)
.LBB0_155:
	v_lshl_add_u64 v[38:39], v[26:27], 0, s[22:23]
	v_add_co_u32_e32 v38, vcc, 0x14100000, v38
	s_mov_b32 s0, 0x358637bd
	s_nop 0
	v_addc_co_u32_e32 v39, vcc, 0, v39, vcc
	global_load_dwordx2 v[40:41], v[38:39], off
	global_load_dwordx2 v[42:43], v[38:39], off offset:512
	global_load_dwordx2 v[44:45], v[38:39], off offset:1024
	s_nop 0
	global_load_dwordx2 v[38:39], v[38:39], off offset:1536
	s_add_u32 s22, s22, 0x800
	s_addc_u32 s23, s23, 0
	s_cmpk_lg_i32 s22, 0x2000
	s_waitcnt vmcnt(3)
	v_lshlrev_b32_e32 v46, 16, v40
	s_waitcnt vmcnt(2)
	v_lshlrev_b32_e32 v47, 16, v42
	v_and_b32_e32 v49, 0xffff0000, v42
	v_and_b32_e32 v48, 0xffff0000, v40
	v_lshlrev_b32_e32 v51, 16, v43
	v_lshlrev_b32_e32 v50, 16, v41
	v_and_b32_e32 v42, 0xffff0000, v41
	v_pk_add_f32 v[40:41], v[46:47], v[48:49]
	v_and_b32_e32 v43, 0xffff0000, v43
	v_pk_add_f32 v[40:41], v[40:41], v[50:51]
	s_waitcnt vmcnt(0)
	v_and_b32_e32 v57, 0xffff0000, v38
	v_pk_add_f32 v[40:41], v[40:41], v[42:43]
	ds_bpermute_b32 v52, v30, v40
	ds_bpermute_b32 v53, v30, v41
	v_and_b32_e32 v56, 0xffff0000, v44
	v_lshlrev_b32_e32 v59, 16, v39
	v_lshlrev_b32_e32 v58, 16, v45
	v_and_b32_e32 v39, 0xffff0000, v39
	s_waitcnt lgkmcnt(0)
	v_pk_add_f32 v[40:41], v[40:41], v[52:53]
	ds_bpermute_b32 v52, v31, v40
	ds_bpermute_b32 v53, v31, v41
	s_waitcnt lgkmcnt(0)
	v_pk_add_f32 v[40:41], v[40:41], v[52:53]
	ds_bpermute_b32 v52, v32, v40
	ds_bpermute_b32 v53, v32, v41
	s_waitcnt lgkmcnt(0)
	v_pk_add_f32 v[40:41], v[40:41], v[52:53]
	ds_bpermute_b32 v52, v33, v40
	ds_bpermute_b32 v53, v33, v41
	s_waitcnt lgkmcnt(0)
	v_pk_add_f32 v[40:41], v[40:41], v[52:53]
	ds_bpermute_b32 v52, v34, v40
	ds_bpermute_b32 v53, v34, v41
	s_waitcnt lgkmcnt(0)
	v_pk_add_f32 v[40:41], v[40:41], v[52:53]
	ds_bpermute_b32 v52, v35, v40
	ds_bpermute_b32 v53, v35, v41
	s_waitcnt lgkmcnt(0)
	v_pk_add_f32 v[40:41], v[40:41], v[52:53]
	s_nop 0
	v_pk_fma_f32 v[48:49], v[40:41], s[8:9], v[48:49] op_sel_hi:[1,0,1] neg_lo:[1,0,0] neg_hi:[1,0,0]
	v_pk_fma_f32 v[46:47], v[40:41], s[8:9], v[46:47] op_sel_hi:[1,0,1] neg_lo:[1,0,0] neg_hi:[1,0,0]
	v_pk_fma_f32 v[50:51], v[40:41], s[8:9], v[50:51] op_sel_hi:[1,0,1] neg_lo:[1,0,0] neg_hi:[1,0,0]
	v_pk_fma_f32 v[40:41], v[40:41], s[8:9], v[42:43] op_sel_hi:[1,0,1] neg_lo:[1,0,0] neg_hi:[1,0,0]
	v_pk_mul_f32 v[42:43], v[48:49], v[48:49]
	s_nop 0
	v_pk_fma_f32 v[42:43], v[46:47], v[46:47], v[42:43]
	s_nop 0
	v_pk_fma_f32 v[42:43], v[50:51], v[50:51], v[42:43]
	s_nop 0
	v_pk_fma_f32 v[42:43], v[40:41], v[40:41], v[42:43]
	ds_bpermute_b32 v52, v30, v42
	ds_bpermute_b32 v53, v30, v43
	s_waitcnt lgkmcnt(0)
	v_pk_add_f32 v[42:43], v[42:43], v[52:53]
	ds_bpermute_b32 v52, v31, v42
	ds_bpermute_b32 v53, v31, v43
	s_waitcnt lgkmcnt(0)
	v_pk_add_f32 v[42:43], v[42:43], v[52:53]
	ds_bpermute_b32 v52, v32, v42
	ds_bpermute_b32 v53, v32, v43
	s_waitcnt lgkmcnt(0)
	v_pk_add_f32 v[42:43], v[42:43], v[52:53]
	ds_bpermute_b32 v52, v33, v42
	ds_bpermute_b32 v53, v33, v43
	s_waitcnt lgkmcnt(0)
	v_pk_add_f32 v[42:43], v[42:43], v[52:53]
	ds_bpermute_b32 v52, v34, v42
	ds_bpermute_b32 v53, v34, v43
	s_waitcnt lgkmcnt(0)
	v_pk_add_f32 v[42:43], v[42:43], v[52:53]
	ds_bpermute_b32 v52, v35, v42
	ds_bpermute_b32 v53, v35, v43
	s_waitcnt lgkmcnt(0)
	v_pk_add_f32 v[42:43], v[42:43], v[52:53]
	v_mov_b64_e32 v[52:53], s[0:1]
	v_pk_fma_f32 v[42:43], v[42:43], s[8:9], v[52:53] op_sel_hi:[1,0,0]
	s_nop 0
	v_mul_f32_e32 v0, 0x4b800000, v42
	v_cmp_gt_f32_e64 s[0:1], s13, v42
	v_cmp_gt_f32_e32 vcc, s13, v43
	s_nop 0
	v_cndmask_b32_e64 v0, v42, v0, s[0:1]
	v_rsq_f32_e32 v42, v0
	v_mul_f32_e32 v0, 0x4b800000, v43
	v_cndmask_b32_e32 v0, v43, v0, vcc
	v_rsq_f32_e32 v43, v0
	s_nop 0
	v_pk_mul_f32 v[54:55], v[42:43], s[6:7] op_sel_hi:[1,0]
	s_nop 0
	v_cndmask_b32_e32 v43, v43, v55, vcc
	v_cndmask_b32_e64 v42, v42, v54, s[0:1]
	v_lshlrev_b32_e32 v55, 16, v38
	v_lshlrev_b32_e32 v54, 16, v44
	v_and_b32_e32 v38, 0xffff0000, v45
	v_pk_add_f32 v[44:45], v[54:55], v[56:57]
	v_pk_mul_f32 v[46:47], v[46:47], v[42:43]
	v_pk_add_f32 v[44:45], v[44:45], v[58:59]
	v_pk_fma_f32 v[46:47], v[20:21], v[46:47], v[18:19]
	v_pk_add_f32 v[44:45], v[44:45], v[38:39]
	ds_bpermute_b32 v60, v30, v44
	ds_bpermute_b32 v61, v30, v45
	v_cvt_pk_bf16_f32 v46, v46, v47
	v_pk_mul_f32 v[48:49], v[48:49], v[42:43]
	v_pk_mul_f32 v[40:41], v[40:41], v[42:43]
	v_pk_fma_f32 v[48:49], v[2:3], v[48:49], v[10:11]
	s_waitcnt lgkmcnt(0)
	v_pk_add_f32 v[44:45], v[44:45], v[60:61]
	ds_bpermute_b32 v60, v31, v44
	ds_bpermute_b32 v61, v31, v45
	v_cvt_pk_bf16_f32 v48, v48, v49
	v_pk_fma_f32 v[40:41], v[4:5], v[40:41], v[12:13]
	s_waitcnt lgkmcnt(0)
	v_pk_add_f32 v[44:45], v[44:45], v[60:61]
	ds_bpermute_b32 v60, v32, v44
	ds_bpermute_b32 v61, v32, v45
	v_cvt_pk_bf16_f32 v40, v40, v41
	s_waitcnt lgkmcnt(0)
	v_pk_add_f32 v[44:45], v[44:45], v[60:61]
	ds_bpermute_b32 v60, v33, v44
	ds_bpermute_b32 v61, v33, v45
	s_waitcnt lgkmcnt(0)
	v_pk_add_f32 v[44:45], v[44:45], v[60:61]
	ds_bpermute_b32 v60, v34, v44
	ds_bpermute_b32 v61, v34, v45
	s_waitcnt lgkmcnt(0)
	v_pk_add_f32 v[44:45], v[44:45], v[60:61]
	ds_bpermute_b32 v60, v35, v44
	ds_bpermute_b32 v61, v35, v45
	s_waitcnt lgkmcnt(0)
	v_pk_add_f32 v[44:45], v[44:45], v[60:61]
	s_nop 0
	v_pk_fma_f32 v[56:57], v[44:45], s[8:9], v[56:57] op_sel_hi:[1,0,1] neg_lo:[1,0,0] neg_hi:[1,0,0]
	v_pk_fma_f32 v[54:55], v[44:45], s[8:9], v[54:55] op_sel_hi:[1,0,1] neg_lo:[1,0,0] neg_hi:[1,0,0]
	v_pk_fma_f32 v[58:59], v[44:45], s[8:9], v[58:59] op_sel_hi:[1,0,1] neg_lo:[1,0,0] neg_hi:[1,0,0]
	v_pk_fma_f32 v[38:39], v[44:45], s[8:9], v[38:39] op_sel_hi:[1,0,1] neg_lo:[1,0,0] neg_hi:[1,0,0]
	v_pk_mul_f32 v[44:45], v[56:57], v[56:57]
	s_nop 0
	v_pk_fma_f32 v[44:45], v[54:55], v[54:55], v[44:45]
	s_nop 0
	v_pk_fma_f32 v[44:45], v[58:59], v[58:59], v[44:45]
	s_nop 0
	v_pk_fma_f32 v[44:45], v[38:39], v[38:39], v[44:45]
	ds_bpermute_b32 v60, v30, v44
	ds_bpermute_b32 v61, v30, v45
	s_waitcnt lgkmcnt(0)
	v_pk_add_f32 v[44:45], v[44:45], v[60:61]
	ds_bpermute_b32 v60, v31, v44
	ds_bpermute_b32 v61, v31, v45
	s_waitcnt lgkmcnt(0)
	v_pk_add_f32 v[44:45], v[44:45], v[60:61]
	ds_bpermute_b32 v60, v32, v44
	ds_bpermute_b32 v61, v32, v45
	s_waitcnt lgkmcnt(0)
	v_pk_add_f32 v[44:45], v[44:45], v[60:61]
	ds_bpermute_b32 v60, v33, v44
	ds_bpermute_b32 v61, v33, v45
	s_waitcnt lgkmcnt(0)
	v_pk_add_f32 v[44:45], v[44:45], v[60:61]
	ds_bpermute_b32 v60, v34, v44
	ds_bpermute_b32 v61, v34, v45
	s_waitcnt lgkmcnt(0)
	v_pk_add_f32 v[44:45], v[44:45], v[60:61]
	ds_bpermute_b32 v60, v35, v44
	ds_bpermute_b32 v61, v35, v45
	s_waitcnt lgkmcnt(0)
	v_pk_add_f32 v[44:45], v[44:45], v[60:61]
	s_nop 0
	v_pk_fma_f32 v[44:45], v[44:45], s[8:9], v[52:53] op_sel_hi:[1,0,0]
	s_nop 0
	v_mul_f32_e32 v0, 0x4b800000, v44
	v_cmp_gt_f32_e64 s[0:1], s13, v44
	v_cmp_gt_f32_e32 vcc, s13, v45
	s_nop 0
	v_cndmask_b32_e64 v0, v44, v0, s[0:1]
	v_rsq_f32_e32 v44, v0
	v_mul_f32_e32 v0, 0x4b800000, v45
	v_cndmask_b32_e32 v0, v45, v0, vcc
	v_rsq_f32_e32 v45, v0
	s_nop 0
	v_pk_mul_f32 v[52:53], v[44:45], s[6:7] op_sel_hi:[1,0]
	s_nop 0
	v_cndmask_b32_e32 v45, v45, v53, vcc
	v_cndmask_b32_e64 v44, v44, v52, s[0:1]
	v_pk_mul_f32 v[52:53], v[54:55], v[44:45]
	v_pk_mul_f32 v[38:39], v[38:39], v[44:45]
	v_pk_fma_f32 v[52:53], v[20:21], v[52:53], v[18:19]
	v_pk_fma_f32 v[38:39], v[4:5], v[38:39], v[12:13]
	v_cvt_pk_bf16_f32 v47, v52, v53
	v_pk_mul_f32 v[52:53], v[56:57], v[44:45]
	v_cvt_pk_bf16_f32 v41, v38, v39
	v_pk_fma_f32 v[52:53], v[2:3], v[52:53], v[10:11]
	s_nop 0
	v_cvt_pk_bf16_f32 v49, v52, v53
	ds_write2_b64 v36, v[46:47], v[48:49] offset1:34
	v_pk_mul_f32 v[46:47], v[50:51], v[42:43]
	v_pk_mul_f32 v[48:49], v[58:59], v[44:45]
	v_pk_fma_f32 v[46:47], v[24:25], v[46:47], v[22:23]
	v_pk_fma_f32 v[48:49], v[24:25], v[48:49], v[22:23]
	v_cvt_pk_bf16_f32 v46, v46, v47
	v_cvt_pk_bf16_f32 v47, v48, v49
	ds_write2_b64 v36, v[46:47], v[40:41] offset0:68 offset1:102
	v_add_u32_e32 v36, 8, v36
	s_cbranch_scc1 .LBB0_155
	s_ashr_i32 s0, s4, 1
	s_andn2_b32 s0, s0, 63
	v_or_b32_e32 v0, s0, v28
	s_movk_i32 s1, 0x110
	v_lshlrev_b32_e32 v2, 1, v29
	v_mul_lo_u32 v0, v0, s1
	v_add3_u32 v0, 0, v2, v0
	s_waitcnt lgkmcnt(0)
	s_barrier
	ds_read_b128 v[2:5], v0 offset:8704
	ds_read_b128 v[10:13], v0
	ds_read_b128 v[126:129], v0 offset:32
	ds_read_b128 v[130:133], v0 offset:8736
	s_waitcnt lgkmcnt(2)
	v_mfma_f32_32x32x16_bf16 v[50:65], v[10:13], v[6:9], 0
	s_mov_b64 s[4:5], 0xa000400
	v_mfma_f32_32x32x16_bf16 v[18:33], v[10:13], v[14:17], 0
	v_mfma_f32_32x32x16_bf16 v[34:49], v[2:5], v[6:9], 0
	v_mfma_f32_32x32x16_bf16 v[2:17], v[2:5], v[14:17], 0
	s_waitcnt lgkmcnt(1)
	v_mfma_f32_32x32x16_bf16 v[50:65], v[126:129], v[106:109], v[50:65]
	v_mfma_f32_32x32x16_bf16 v[18:33], v[126:129], v[118:121], v[18:33]
	s_waitcnt lgkmcnt(0)
	v_mfma_f32_32x32x16_bf16 v[34:49], v[130:133], v[106:109], v[34:49]
	v_mfma_f32_32x32x16_bf16 v[2:17], v[130:133], v[118:121], v[2:17]
	ds_read_b128 v[106:109], v0 offset:64
	ds_read_b128 v[118:121], v0 offset:8768
	s_waitcnt lgkmcnt(1)
	v_mfma_f32_32x32x16_bf16 v[50:65], v[106:109], v[98:101], v[50:65]
	v_mfma_f32_32x32x16_bf16 v[18:33], v[106:109], v[114:117], v[18:33]
	s_waitcnt lgkmcnt(0)
	v_mfma_f32_32x32x16_bf16 v[34:49], v[118:121], v[98:101], v[34:49]
	ds_read_b128 v[98:101], v0 offset:96
	ds_read_b128 v[106:109], v0 offset:8800
	v_mfma_f32_32x32x16_bf16 v[2:17], v[118:121], v[114:117], v[2:17]
	s_waitcnt lgkmcnt(1)
	v_mfma_f32_32x32x16_bf16 v[50:65], v[98:101], v[90:93], v[50:65]
	v_mfma_f32_32x32x16_bf16 v[18:33], v[98:101], v[110:113], v[18:33]
	s_waitcnt lgkmcnt(0)
	v_mfma_f32_32x32x16_bf16 v[34:49], v[106:109], v[90:93], v[34:49]
	ds_read_b128 v[90:93], v0 offset:128
	ds_read_b128 v[98:101], v0 offset:8832
	v_mfma_f32_32x32x16_bf16 v[2:17], v[106:109], v[110:113], v[2:17]
	s_waitcnt lgkmcnt(1)
	v_mfma_f32_32x32x16_bf16 v[50:65], v[90:93], v[82:85], v[50:65]
	v_mfma_f32_32x32x16_bf16 v[18:33], v[90:93], v[102:105], v[18:33]
	s_waitcnt lgkmcnt(0)
	v_mfma_f32_32x32x16_bf16 v[34:49], v[98:101], v[82:85], v[34:49]
	ds_read_b128 v[82:85], v0 offset:160
	ds_read_b128 v[90:93], v0 offset:8864
	v_mfma_f32_32x32x16_bf16 v[2:17], v[98:101], v[102:105], v[2:17]
	s_waitcnt lgkmcnt(1)
	v_mfma_f32_32x32x16_bf16 v[50:65], v[82:85], v[74:77], v[50:65]
	v_mfma_f32_32x32x16_bf16 v[18:33], v[82:85], v[94:97], v[18:33]
	s_waitcnt lgkmcnt(0)
	v_mfma_f32_32x32x16_bf16 v[34:49], v[90:93], v[74:77], v[34:49]
	ds_read_b128 v[74:77], v0 offset:192
	ds_read_b128 v[82:85], v0 offset:8896
	v_mfma_f32_32x32x16_bf16 v[2:17], v[90:93], v[94:97], v[2:17]
	s_waitcnt lgkmcnt(1)
	v_mfma_f32_32x32x16_bf16 v[50:65], v[74:77], v[70:73], v[50:65]
	v_mfma_f32_32x32x16_bf16 v[18:33], v[74:77], v[86:89], v[18:33]
	s_waitcnt lgkmcnt(0)
	v_mfma_f32_32x32x16_bf16 v[34:49], v[82:85], v[70:73], v[34:49]
	ds_read_b128 v[70:73], v0 offset:224
	ds_read_b128 v[74:77], v0 offset:8928
	v_or_b32_e32 v0, s3, v122
	s_ashr_i32 s3, s2, 31
	v_mfma_f32_32x32x16_bf16 v[2:17], v[82:85], v[86:89], v[2:17]
	s_waitcnt lgkmcnt(1)
	v_mfma_f32_32x32x16_bf16 v[50:65], v[70:73], v[66:69], v[50:65]
	v_mfma_f32_32x32x16_bf16 v[18:33], v[70:73], v[78:81], v[18:33]
	v_lshl_or_b32 v72, v123, 2, s0
	v_readlane_b32 s0, v253, 11
	v_readlane_b32 s1, v253, 12
	v_ashrrev_i32_e32 v73, 31, v72
	v_mov_b32_e32 v123, v1
	s_waitcnt lgkmcnt(0)
	v_mfma_f32_32x32x16_bf16 v[34:49], v[74:77], v[66:69], v[34:49]
	v_lshl_add_u64 v[66:67], v[124:125], 2, s[68:69]
	global_load_dword v68, v[66:67], off
	v_lshlrev_b64 v[66:67], 9, v[0:1]
	s_waitcnt vmcnt(0)
	v_add_f32_e64 v50, v50, v68
	v_add_f32_e64 v51, v51, v68
	v_mfma_f32_32x32x16_bf16 v[2:17], v[74:77], v[78:81], v[2:17]
	v_lshl_add_u64 v[74:75], s[0:1], 0, v[66:67]
	v_lshlrev_b64 v[66:67], 11, v[0:1]
	v_lshl_add_u64 v[66:67], s[88:89], 0, v[66:67]
	v_lshl_add_u64 v[70:71], v[66:67], 0, s[4:5]
	v_lshlrev_b64 v[66:67], 1, v[72:73]
	v_lshl_add_u64 v[74:75], v[74:75], 0, v[66:67]
	global_load_dwordx2 v[78:79], v[74:75], off
	global_load_dwordx2 v[126:127], v[74:75], off offset:16
	global_load_dwordx2 v[128:129], v[74:75], off offset:32
	global_load_dwordx2 v[130:131], v[74:75], off offset:48
	global_load_dwordx2 v[132:133], v[74:75], off offset:64
	global_load_dwordx2 v[134:135], v[74:75], off offset:80
	global_load_dwordx2 v[136:137], v[74:75], off offset:96
	global_load_dwordx2 v[138:139], v[74:75], off offset:112
	v_pk_add_f32 v[52:53], v[52:53], v[68:69] op_sel_hi:[1,0]
	v_pk_add_f32 v[54:55], v[54:55], v[68:69] op_sel_hi:[1,0]
	v_pk_add_f32 v[56:57], v[56:57], v[68:69] op_sel_hi:[1,0]
	v_pk_add_f32 v[58:59], v[58:59], v[68:69] op_sel_hi:[1,0]
	v_pk_add_f32 v[34:35], v[34:35], v[68:69] op_sel_hi:[1,0]
	v_or_b32_e32 v76, 32, v72
	v_pk_add_f32 v[36:37], v[36:37], v[68:69] op_sel_hi:[1,0]
	v_ashrrev_i32_e32 v77, 31, v76
	v_pk_add_f32 v[38:39], v[38:39], v[68:69] op_sel_hi:[1,0]
	v_pk_add_f32 v[40:41], v[40:41], v[68:69] op_sel_hi:[1,0]
	v_pk_add_f32 v[42:43], v[42:43], v[68:69] op_sel_hi:[1,0]
	v_pk_add_f32 v[44:45], v[44:45], v[68:69] op_sel_hi:[1,0]
	v_pk_add_f32 v[46:47], v[46:47], v[68:69] op_sel_hi:[1,0]
	v_or_b32_e32 v0, 32, v0
	s_waitcnt vmcnt(7)
	v_lshlrev_b32_e32 v80, 16, v78
	v_and_b32_e32 v81, 0xffff0000, v78
	v_lshlrev_b32_e32 v78, 16, v79
	v_and_b32_e32 v79, 0xffff0000, v79
	v_pk_mul_f32 v[50:51], v[50:51], v[80:81]
	v_pk_mul_f32 v[52:53], v[52:53], v[78:79]
	v_cvt_pk_bf16_f32 v50, v50, v51
	v_cvt_pk_bf16_f32 v51, v52, v53
	v_lshl_add_u64 v[52:53], v[70:71], 0, v[66:67]
	global_store_dwordx2 v[52:53], v[50:51], off
	s_waitcnt vmcnt(7)
	v_mov_b64_e32 v[52:53], v[126:127]
	v_or_b32_e32 v50, 8, v72
	v_ashrrev_i32_e32 v51, 31, v50
	v_lshlrev_b64 v[50:51], 1, v[50:51]
	v_lshlrev_b32_e32 v78, 16, v52
	v_and_b32_e32 v79, 0xffff0000, v52
	v_pk_mul_f32 v[54:55], v[54:55], v[78:79]
	s_nop 0
	v_cvt_pk_bf16_f32 v52, v54, v55
	v_lshlrev_b32_e32 v54, 16, v53
	v_and_b32_e32 v55, 0xffff0000, v53
	v_pk_mul_f32 v[54:55], v[56:57], v[54:55]
	s_nop 0
	v_cvt_pk_bf16_f32 v53, v54, v55
	v_lshl_add_u64 v[54:55], v[70:71], 0, v[50:51]
	global_store_dwordx2 v[54:55], v[52:53], off
	s_waitcnt vmcnt(7)
	v_mov_b64_e32 v[54:55], v[128:129]
	v_or_b32_e32 v52, 16, v72
	v_ashrrev_i32_e32 v53, 31, v52
	v_lshlrev_b64 v[52:53], 1, v[52:53]
	v_lshlrev_b32_e32 v56, 16, v54
	v_and_b32_e32 v57, 0xffff0000, v54
	v_pk_mul_f32 v[56:57], v[58:59], v[56:57]
	v_pk_add_f32 v[58:59], v[60:61], v[68:69] op_sel_hi:[1,0]
	v_cvt_pk_bf16_f32 v54, v56, v57
	v_lshlrev_b32_e32 v56, 16, v55
	v_and_b32_e32 v57, 0xffff0000, v55
	v_pk_mul_f32 v[56:57], v[58:59], v[56:57]
	v_pk_add_f32 v[60:61], v[62:63], v[68:69] op_sel_hi:[1,0]
	v_cvt_pk_bf16_f32 v55, v56, v57
	v_lshl_add_u64 v[56:57], v[70:71], 0, v[52:53]
	global_store_dwordx2 v[56:57], v[54:55], off
	s_waitcnt vmcnt(7)
	v_mov_b64_e32 v[56:57], v[130:131]
	v_or_b32_e32 v54, 24, v72
	v_ashrrev_i32_e32 v55, 31, v54
	v_lshlrev_b64 v[54:55], 1, v[54:55]
	v_lshlrev_b32_e32 v58, 16, v56
	v_and_b32_e32 v59, 0xffff0000, v56
	v_pk_mul_f32 v[58:59], v[60:61], v[58:59]
	v_pk_add_f32 v[60:61], v[64:65], v[68:69] op_sel_hi:[1,0]
	v_cvt_pk_bf16_f32 v56, v58, v59
	v_lshlrev_b32_e32 v58, 16, v57
	v_and_b32_e32 v59, 0xffff0000, v57
	v_pk_mul_f32 v[58:59], v[60:61], v[58:59]
	s_nop 0
	v_cvt_pk_bf16_f32 v57, v58, v59
	v_lshl_add_u64 v[58:59], v[70:71], 0, v[54:55]
	global_store_dwordx2 v[58:59], v[56:57], off
	s_waitcnt vmcnt(7)
	v_mov_b64_e32 v[56:57], v[132:133]
	v_lshlrev_b32_e32 v58, 16, v56
	v_and_b32_e32 v59, 0xffff0000, v56
	v_pk_mul_f32 v[34:35], v[34:35], v[58:59]
	s_nop 0
	v_cvt_pk_bf16_f32 v56, v34, v35
	v_lshlrev_b32_e32 v34, 16, v57
	v_and_b32_e32 v35, 0xffff0000, v57
	v_pk_mul_f32 v[34:35], v[36:37], v[34:35]
	s_nop 0
	v_cvt_pk_bf16_f32 v57, v34, v35
	v_lshlrev_b64 v[34:35], 1, v[76:77]
	v_lshl_add_u64 v[36:37], v[70:71], 0, v[34:35]
	global_store_dwordx2 v[36:37], v[56:57], off
	s_waitcnt vmcnt(7)
	v_mov_b64_e32 v[56:57], v[134:135]
	v_or_b32_e32 v36, 40, v72
	v_ashrrev_i32_e32 v37, 31, v36
	v_lshlrev_b64 v[36:37], 1, v[36:37]
	v_lshlrev_b32_e32 v58, 16, v56
	v_and_b32_e32 v59, 0xffff0000, v56
	v_lshlrev_b32_e32 v56, 16, v57
	v_and_b32_e32 v57, 0xffff0000, v57
	v_pk_mul_f32 v[38:39], v[38:39], v[58:59]
	v_pk_mul_f32 v[40:41], v[40:41], v[56:57]
	v_cvt_pk_bf16_f32 v38, v38, v39
	v_cvt_pk_bf16_f32 v39, v40, v41
	v_lshl_add_u64 v[40:41], v[70:71], 0, v[36:37]
	global_store_dwordx2 v[40:41], v[38:39], off
	s_waitcnt vmcnt(7)
	v_mov_b64_e32 v[40:41], v[136:137]
	v_or_b32_e32 v38, 48, v72
	v_ashrrev_i32_e32 v39, 31, v38
	v_lshlrev_b64 v[38:39], 1, v[38:39]
	v_lshlrev_b32_e32 v56, 16, v40
	v_and_b32_e32 v57, 0xffff0000, v40
	v_pk_mul_f32 v[42:43], v[42:43], v[56:57]
	s_nop 0
	v_cvt_pk_bf16_f32 v40, v42, v43
	v_lshlrev_b32_e32 v42, 16, v41
	v_and_b32_e32 v43, 0xffff0000, v41
	v_pk_mul_f32 v[42:43], v[44:45], v[42:43]
	s_nop 0
	v_cvt_pk_bf16_f32 v41, v42, v43
	v_lshl_add_u64 v[42:43], v[70:71], 0, v[38:39]
	global_store_dwordx2 v[42:43], v[40:41], off
	s_waitcnt vmcnt(7)
	v_mov_b64_e32 v[42:43], v[138:139]
	v_or_b32_e32 v40, 56, v72
	v_ashrrev_i32_e32 v41, 31, v40
	v_lshlrev_b64 v[40:41], 1, v[40:41]
	v_lshlrev_b32_e32 v44, 16, v42
	v_and_b32_e32 v45, 0xffff0000, v42
	v_pk_mul_f32 v[44:45], v[46:47], v[44:45]
	v_pk_add_f32 v[46:47], v[48:49], v[68:69] op_sel_hi:[1,0]
	v_cvt_pk_bf16_f32 v42, v44, v45
	v_lshlrev_b32_e32 v44, 16, v43
	v_and_b32_e32 v45, 0xffff0000, v43
	v_pk_mul_f32 v[44:45], v[46:47], v[44:45]
	s_nop 0
	v_cvt_pk_bf16_f32 v43, v44, v45
	v_lshl_add_u64 v[44:45], v[70:71], 0, v[40:41]
	global_store_dwordx2 v[44:45], v[42:43], off
	v_lshlrev_b64 v[44:45], 9, v[0:1]
	v_lshl_add_u64 v[42:43], v[122:123], 0, s[2:3]
	v_lshl_add_u64 v[46:47], s[0:1], 0, v[44:45]
	v_lshl_add_u64 v[42:43], v[42:43], 2, s[68:69]
	v_lshl_add_u64 v[46:47], v[46:47], 0, v[66:67]
	global_load_dword v42, v[42:43], off offset:128
	v_lshlrev_b64 v[44:45], 11, v[0:1]
	global_load_dwordx2 v[48:49], v[46:47], off
	global_load_dwordx2 v[140:141], v[46:47], off offset:16
	global_load_dwordx2 v[142:143], v[46:47], off offset:32
	global_load_dwordx2 v[144:145], v[46:47], off offset:48
	global_load_dwordx2 v[146:147], v[46:47], off offset:64
	global_load_dwordx2 v[148:149], v[46:47], off offset:80
	global_load_dwordx2 v[150:151], v[46:47], off offset:96
	global_load_dwordx2 v[152:153], v[46:47], off offset:112
	v_lshl_add_u64 v[44:45], s[88:89], 0, v[44:45]
	v_lshl_add_u64 v[44:45], v[44:45], 0, s[4:5]
	s_waitcnt vmcnt(8)
	v_pk_add_f32 v[18:19], v[18:19], v[42:43] op_sel_hi:[1,0]
	v_pk_add_f32 v[20:21], v[20:21], v[42:43] op_sel_hi:[1,0]
	s_waitcnt vmcnt(7)
	v_lshlrev_b32_e32 v56, 16, v48
	v_and_b32_e32 v57, 0xffff0000, v48
	v_lshlrev_b32_e32 v48, 16, v49
	v_and_b32_e32 v49, 0xffff0000, v49
	v_pk_mul_f32 v[18:19], v[18:19], v[56:57]
	v_pk_mul_f32 v[20:21], v[20:21], v[48:49]
	v_cvt_pk_bf16_f32 v18, v18, v19
	v_cvt_pk_bf16_f32 v19, v20, v21
	v_lshl_add_u64 v[20:21], v[44:45], 0, v[66:67]
	global_store_dwordx2 v[20:21], v[18:19], off
	s_waitcnt vmcnt(7)
	v_mov_b64_e32 v[18:19], v[140:141]
	v_pk_add_f32 v[22:23], v[22:23], v[42:43] op_sel_hi:[1,0]
	v_pk_add_f32 v[2:3], v[2:3], v[42:43] op_sel_hi:[1,0]
	v_pk_add_f32 v[4:5], v[4:5], v[42:43] op_sel_hi:[1,0]
	v_pk_add_f32 v[6:7], v[6:7], v[42:43] op_sel_hi:[1,0]
	v_lshlrev_b32_e32 v20, 16, v18
	v_and_b32_e32 v21, 0xffff0000, v18
	v_pk_mul_f32 v[20:21], v[22:23], v[20:21]
	v_pk_add_f32 v[22:23], v[24:25], v[42:43] op_sel_hi:[1,0]
	v_cvt_pk_bf16_f32 v18, v20, v21
	v_lshlrev_b32_e32 v20, 16, v19
	v_and_b32_e32 v21, 0xffff0000, v19
	v_pk_mul_f32 v[20:21], v[22:23], v[20:21]
	v_pk_add_f32 v[22:23], v[26:27], v[42:43] op_sel_hi:[1,0]
	v_cvt_pk_bf16_f32 v19, v20, v21
	v_lshl_add_u64 v[20:21], v[44:45], 0, v[50:51]
	global_store_dwordx2 v[20:21], v[18:19], off
	s_waitcnt vmcnt(7)
	v_mov_b64_e32 v[18:19], v[142:143]
	v_lshlrev_b32_e32 v20, 16, v18
	v_and_b32_e32 v21, 0xffff0000, v18
	v_pk_mul_f32 v[20:21], v[22:23], v[20:21]
	v_pk_add_f32 v[22:23], v[28:29], v[42:43] op_sel_hi:[1,0]
	v_cvt_pk_bf16_f32 v18, v20, v21
	v_lshlrev_b32_e32 v20, 16, v19
	v_and_b32_e32 v21, 0xffff0000, v19
	v_pk_mul_f32 v[20:21], v[22:23], v[20:21]
	v_pk_add_f32 v[22:23], v[30:31], v[42:43] op_sel_hi:[1,0]
	v_cvt_pk_bf16_f32 v19, v20, v21
	v_lshl_add_u64 v[20:21], v[44:45], 0, v[52:53]
	global_store_dwordx2 v[20:21], v[18:19], off
	s_waitcnt vmcnt(7)
	v_mov_b64_e32 v[18:19], v[144:145]
	v_lshlrev_b32_e32 v20, 16, v18
	v_and_b32_e32 v21, 0xffff0000, v18
	v_pk_mul_f32 v[20:21], v[22:23], v[20:21]
	v_pk_add_f32 v[22:23], v[32:33], v[42:43] op_sel_hi:[1,0]
	v_cvt_pk_bf16_f32 v18, v20, v21
	v_lshlrev_b32_e32 v20, 16, v19
	v_and_b32_e32 v21, 0xffff0000, v19
	v_pk_mul_f32 v[20:21], v[22:23], v[20:21]
	s_nop 0
	v_cvt_pk_bf16_f32 v19, v20, v21
	v_lshl_add_u64 v[20:21], v[44:45], 0, v[54:55]
	global_store_dwordx2 v[20:21], v[18:19], off
	s_waitcnt vmcnt(7)
	v_mov_b64_e32 v[18:19], v[146:147]
	v_lshlrev_b32_e32 v20, 16, v18
	v_and_b32_e32 v21, 0xffff0000, v18
	v_lshlrev_b32_e32 v18, 16, v19
	v_and_b32_e32 v19, 0xffff0000, v19
	v_pk_mul_f32 v[2:3], v[2:3], v[20:21]
	v_pk_mul_f32 v[4:5], v[4:5], v[18:19]
	v_cvt_pk_bf16_f32 v2, v2, v3
	v_cvt_pk_bf16_f32 v3, v4, v5
	v_lshl_add_u64 v[4:5], v[44:45], 0, v[34:35]
	global_store_dwordx2 v[4:5], v[2:3], off
	s_waitcnt vmcnt(7)
	v_mov_b64_e32 v[2:3], v[148:149]
	v_lshlrev_b32_e32 v4, 16, v2
	v_and_b32_e32 v5, 0xffff0000, v2
	v_pk_mul_f32 v[4:5], v[6:7], v[4:5]
	v_pk_add_f32 v[6:7], v[8:9], v[42:43] op_sel_hi:[1,0]
	v_cvt_pk_bf16_f32 v2, v4, v5
	v_lshlrev_b32_e32 v4, 16, v3
	v_and_b32_e32 v5, 0xffff0000, v3
	v_pk_mul_f32 v[4:5], v[6:7], v[4:5]
	v_pk_add_f32 v[6:7], v[10:11], v[42:43] op_sel_hi:[1,0]
	v_cvt_pk_bf16_f32 v3, v4, v5
	v_lshl_add_u64 v[4:5], v[44:45], 0, v[36:37]
	global_store_dwordx2 v[4:5], v[2:3], off
	s_waitcnt vmcnt(7)
	v_mov_b64_e32 v[2:3], v[150:151]
	v_lshlrev_b32_e32 v4, 16, v2
	v_and_b32_e32 v5, 0xffff0000, v2
	v_pk_mul_f32 v[4:5], v[6:7], v[4:5]
	v_pk_add_f32 v[6:7], v[12:13], v[42:43] op_sel_hi:[1,0]
	v_cvt_pk_bf16_f32 v2, v4, v5
	v_lshlrev_b32_e32 v4, 16, v3
	v_and_b32_e32 v5, 0xffff0000, v3
	v_pk_mul_f32 v[4:5], v[6:7], v[4:5]
	v_pk_add_f32 v[6:7], v[14:15], v[42:43] op_sel_hi:[1,0]
	v_cvt_pk_bf16_f32 v3, v4, v5
	v_lshl_add_u64 v[4:5], v[44:45], 0, v[38:39]
	global_store_dwordx2 v[4:5], v[2:3], off
	s_waitcnt vmcnt(7)
	v_mov_b64_e32 v[2:3], v[152:153]
	v_lshlrev_b32_e32 v4, 16, v2
	v_and_b32_e32 v5, 0xffff0000, v2
	v_pk_mul_f32 v[4:5], v[6:7], v[4:5]
	v_pk_add_f32 v[6:7], v[16:17], v[42:43] op_sel_hi:[1,0]
	v_cvt_pk_bf16_f32 v2, v4, v5
	v_lshlrev_b32_e32 v4, 16, v3
	v_and_b32_e32 v5, 0xffff0000, v3
	v_pk_mul_f32 v[4:5], v[6:7], v[4:5]
	s_nop 0
	v_cvt_pk_bf16_f32 v3, v4, v5
	v_lshl_add_u64 v[4:5], v[44:45], 0, v[40:41]
	global_store_dwordx2 v[4:5], v[2:3], off

.Ldl_ctxaddr:
	s_sub_i32 s20, s3, 63
	s_lshl_b64 s[4:5], s[20:21], 15
	v_lshl_add_u64 v[66:67], v[172:173], 0, s[4:5]
	s_branch .LBB0_232
	s_nop 0
	s_nop 0
	s_nop 0
	s_nop 0
	s_nop 0
	s_nop 0
	s_nop 0
	s_nop 0
	s_nop 0
	s_nop 0
	s_nop 0
	s_nop 0
	s_nop 0
	s_nop 0
	s_nop 0
	s_nop 0
	s_nop 0
	s_nop 0
.LBB0_229:
	v_mov_b64_e32 v[174:175], v[182:183]
	s_cmpk_lg_i32 s3, 0x43
	s_cselect_b64 s[0:1], -1, 0
	s_cmpk_eq_i32 s3, 0x43
	s_cbranch_scc1 .LBB0_233
